# grid barrier release flattened: non-leader workgroups poll the cross-XCD generation word directly (one hop fewer)
# speedup vs baseline: 1.0020x; 1.0020x over previous
.LBB0_128:
	s_or_b64 exec, exec, s[12:13]
	v_cvt_f32_u32_e32 v4, v2
	s_waitcnt vmcnt(0)
	v_readfirstlane_b32 s0, v3
	v_sub_u32_e32 v3, 0, v2
	v_rcp_iflag_f32_e32 v4, v4
	v_add_u32_e32 v5, s0, v1
	v_mul_f32_e32 v4, 0x4f7ffffe, v4
	v_cvt_u32_f32_e32 v4, v4
	v_mul_lo_u32 v1, v3, v4
	v_mul_hi_u32 v1, v4, v1
	v_add_u32_e32 v1, v4, v1
	v_mul_hi_u32 v1, v5, v1
	v_mul_lo_u32 v3, v1, v2
	v_sub_u32_e32 v3, v5, v3
	v_add_u32_e32 v4, 1, v1
	v_cmp_ge_u32_e32 vcc, v3, v2
	s_nop 1
	v_cndmask_b32_e32 v1, v1, v4, vcc
	v_sub_u32_e32 v4, v3, v2
	v_cndmask_b32_e32 v3, v3, v4, vcc
	v_add_u32_e32 v4, 1, v1
	v_cmp_ge_u32_e32 vcc, v3, v2
	v_add_u32_e32 v3, 1, v5
	s_nop 0
	v_cndmask_b32_e32 v1, v1, v4, vcc
	v_mul_lo_u32 v4, v2, v1
	v_add_u32_e32 v2, v4, v2
	v_cmp_ne_u32_e32 vcc, v3, v2
	s_and_saveexec_b64 s[0:1], vcc
	s_xor_b64 s[10:11], exec, s[0:1]
	s_cbranch_execz .LBB0_142
	s_waitcnt lgkmcnt(0)
	v_mov_b32_e32 v0, 0x7500
	global_load_dword v0, v0, s[6:7] sc1
	s_add_u32 s16, s6, 0x7500
	s_addc_u32 s17, s7, 0
	s_waitcnt vmcnt(0)
	v_cmp_eq_u32_e32 vcc, v0, v1
	s_and_saveexec_b64 s[12:13], vcc
	s_cbranch_execz .LBB0_141
	s_add_u32 s14, s6, 0x4200
	s_addc_u32 s15, s7, 0
	s_mov_b32 s0, 1
	s_mov_b64 s[18:19], 0
	v_mov_b32_e32 v0, 0
	s_branch .LBB0_132
